# attention loop: next K/V tile global loads issued at half-step start into loop-dead registers (whole half-step to land) on top of v11 stack
# baseline (speedup 1.0000x reference)
; __device__ __forceinline__ void finishSM(f32x16& p0, f32x16& p1, float alpha, float& l_reg, bf16x8& pa0, bf16x8& pa1, bf16x8& pa2, bf16x8& pa3) {
;     for (int r = 0; r < 16; ++r) p1[r] = __builtin_amdgcn_exp2f(p1[r]);
;     float ps = 0; for (int r = 0; r < 16; ++r) ps += p0[r]; for (int r = 0; r < 16; ++r) ps += p1[r];
;     { auto rr = __builtin_amdgcn_permlane32_swap(__float_as_uint(ps), __float_as_uint(ps), false, false);
;       ps = __uint_as_float(rr[0]) + __uint_as_float(rr[1]); }
;     l_reg = l_reg * alpha + ps;
;     ...
;     PK4(p0, 0, pa0); PK4(p0, 8, pa1); PK4(p1, 0, pa2); PK4(p1, 8, pa3);
; template <int KB>
; __device__ __forceinline__ void qkt(f32x16& p0, f32x16& p1, const char* K_lds, int r32, int hi, const bf16x8* qr) {
;     p0 = f32x16{}; p1 = f32x16{};
;     const char* kb[4];
; #pragma unroll
;     for (int dd = 0; dd < 4; ++dd) kb[dd] = K_lds + KB * SHM_K + KSWZ(r32, (dd * 16 + hi * 8) * 2);
; #pragma unroll
;     for (int d0 = 0; d0 < 8; ++d0) { const char* a = kb[d0 & 3] + (d0 >> 2) * 128;
;         bf16x8 b0 = *reinterpret_cast<const bf16x8*>(a);
;         bf16x8 b1 = *reinterpret_cast<const bf16x8*>(a + 32 * 256);
;         p0 = __builtin_amdgcn_mfma_f32_32x32x16_bf16(b0, qr[d0], p0, 0, 0, 0);
;         p1 = __builtin_amdgcn_mfma_f32_32x32x16_bf16(b1, qr[d0], p1, 0, 0, 0); }
; }
.LBB0_89:
	v_add_u32_e32 v250, s7, v166
	v_add_u32_e32 v234, 1, v250
	v_add_u32_e32 v236, 33, v250
	v_ashrrev_i32_e32 v235, 31, v234
	v_ashrrev_i32_e32 v237, 31, v236
	v_lshlrev_b64 v[242:243], 8, v[234:235]
	v_lshlrev_b64 v[244:245], 8, v[236:237]
	v_lshl_add_u64 v[234:235], v[170:171], 0, v[242:243]
	v_lshl_add_u64 v[238:239], v[170:171], 0, v[244:245]
	v_lshl_add_u64 v[242:243], v[176:177], 0, v[242:243]
	v_lshl_add_u64 v[246:247], v[176:177], 0, v[244:245]
	global_load_dwordx4 v[234:237], v[234:235], off
	s_nop 0
	global_load_dwordx4 v[238:241], v[238:239], off
	s_nop 0
	global_load_dwordx4 v[242:245], v[242:243], off
	s_nop 0
	global_load_dwordx4 v[246:249], v[246:247], off
	ds_read_b128 v[66:69], v169 offset:49152
	ds_read_b128 v[70:73], v169 offset:57344
	ds_read_b128 v[100:103], v193 offset:49152
	ds_read_b128 v[136:139], v193 offset:57344
	v_add_f32_e32 v148, 0, v231
	v_add_f32_e32 v148, v233, v148
	s_waitcnt lgkmcnt(3)
	v_mfma_f32_32x32x16_bf16 v[82:97], v[66:69], v[132:135], 0
	v_add_f32_e32 v148, v229, v148
	v_add_f32_e32 v148, v232, v148
	v_add_f32_e32 v148, v228, v148
	v_add_f32_e32 v148, v230, v148
	v_add_f32_e32 v148, v226, v148
	v_add_f32_e32 v148, v227, v148
	v_add_f32_e32 v148, v223, v148
	s_waitcnt lgkmcnt(2)
	v_mfma_f32_32x32x16_bf16 v[66:81], v[70:73], v[132:135], 0
	v_add_f32_e32 v148, v225, v148
	v_add_f32_e32 v148, v209, v148
	v_add_f32_e32 v148, v224, v148
	v_add_f32_e32 v148, v206, v148
	v_add_f32_e32 v148, v208, v148
	v_add_f32_e32 v148, v205, v148
	v_add_f32_e32 v148, v207, v148
	s_waitcnt lgkmcnt(1)
	v_mfma_f32_32x32x16_bf16 v[82:97], v[100:103], v[128:131], v[82:97]
	v_exp_f32_e32 v140, v152
	v_exp_f32_e32 v141, v153
	v_exp_f32_e32 v142, v180
	v_exp_f32_e32 v143, v181
	v_exp_f32_e32 v144, v160
	v_exp_f32_e32 v145, v161
	v_exp_f32_e32 v146, v154
	s_waitcnt lgkmcnt(0)
	v_mfma_f32_32x32x16_bf16 v[66:81], v[136:139], v[128:131], v[66:81]
	ds_read_b128 v[100:103], v194 offset:49152
	ds_read_b128 v[136:139], v194 offset:57344
	v_exp_f32_e32 v147, v155
	s_waitcnt lgkmcnt(1)
	v_mfma_f32_32x32x16_bf16 v[82:97], v[100:103], v[124:127], v[82:97]
	s_waitcnt lgkmcnt(0)
	v_mfma_f32_32x32x16_bf16 v[66:81], v[136:139], v[124:127], v[66:81]
	ds_read_b128 v[100:103], v195 offset:49152
	ds_read_b128 v[136:139], v195 offset:57344
	s_waitcnt lgkmcnt(1)
	v_mfma_f32_32x32x16_bf16 v[82:97], v[100:103], v[120:123], v[82:97]
	s_waitcnt lgkmcnt(0)
	v_mfma_f32_32x32x16_bf16 v[66:81], v[136:139], v[120:123], v[66:81]
	ds_read_b128 v[100:103], v169 offset:49280
	ds_read_b128 v[136:139], v169 offset:57472
	s_waitcnt lgkmcnt(1)
	v_mfma_f32_32x32x16_bf16 v[82:97], v[100:103], v[116:119], v[82:97]
	s_waitcnt lgkmcnt(0)
	v_mfma_f32_32x32x16_bf16 v[66:81], v[136:139], v[116:119], v[66:81]
	ds_read_b128 v[100:103], v193 offset:49280
	ds_read_b128 v[136:139], v193 offset:57472
	s_waitcnt lgkmcnt(1)
	v_mfma_f32_32x32x16_bf16 v[82:97], v[100:103], v[112:115], v[82:97]
	s_waitcnt lgkmcnt(0)
	v_mfma_f32_32x32x16_bf16 v[66:81], v[136:139], v[112:115], v[66:81]
	ds_read_b128 v[100:103], v194 offset:49280
	ds_read_b128 v[136:139], v194 offset:57472
	s_waitcnt lgkmcnt(1)
	v_mfma_f32_32x32x16_bf16 v[82:97], v[100:103], v[108:111], v[82:97]
	s_waitcnt lgkmcnt(0)
	v_mfma_f32_32x32x16_bf16 v[66:81], v[136:139], v[108:111], v[66:81]
	ds_read_b128 v[100:103], v195 offset:49280
	ds_read_b128 v[136:139], v195 offset:57472
	s_waitcnt lgkmcnt(1)
	v_mfma_f32_32x32x16_bf16 v[82:97], v[100:103], v[104:107], v[82:97]
	v_exp_f32_e32 v100, v178
	v_exp_f32_e32 v101, v179
	v_exp_f32_e32 v102, v162
	v_exp_f32_e32 v103, v163
	v_add_f32_e32 v148, v100, v148
	v_add_f32_e32 v148, v101, v148
	v_add_f32_e32 v148, v102, v148
	s_waitcnt lgkmcnt(0)
	v_mfma_f32_32x32x16_bf16 v[66:81], v[136:139], v[104:107], v[66:81]
	v_exp_f32_e32 v136, v158
	v_exp_f32_e32 v137, v159
	v_exp_f32_e32 v138, v156
	v_exp_f32_e32 v139, v157
	v_add_f32_e32 v148, v103, v148
	v_add_f32_e32 v148, v136, v148
	v_add_f32_e32 v148, v137, v148
	v_add_f32_e32 v148, v138, v148
	v_add_f32_e32 v148, v139, v148
	v_add_f32_e32 v148, v140, v148
	v_add_f32_e32 v148, v141, v148
	v_add_f32_e32 v148, v142, v148
	v_add_f32_e32 v148, v143, v148
	v_add_f32_e32 v148, v144, v148
	v_add_f32_e32 v148, v145, v148
	v_add_f32_e32 v148, v146, v148
	v_add_f32_e32 v199, v147, v148
	v_mov_b32_e32 v200, v199
	s_nop 1
	v_permlane32_swap_b32_e32 v199, v200
	v_cvt_pk_bf16_f32 v148, v231, v233
	v_cvt_pk_bf16_f32 v149, v229, v232
	v_cvt_pk_bf16_f32 v150, v228, v230
	v_cvt_pk_bf16_f32 v151, v226, v227
	v_cvt_pk_bf16_f32 v152, v223, v225
	v_cvt_pk_bf16_f32 v153, v209, v224
	v_cvt_pk_bf16_f32 v154, v206, v208
	v_cvt_pk_bf16_f32 v155, v205, v207
	v_cvt_pk_bf16_f32 v156, v100, v101
	v_cvt_pk_bf16_f32 v157, v102, v103
	v_cvt_pk_bf16_f32 v158, v136, v137
	v_cvt_pk_bf16_f32 v159, v138, v139
	v_cvt_pk_bf16_f32 v160, v140, v141
	v_cvt_pk_bf16_f32 v161, v142, v143
	v_cvt_pk_bf16_f32 v162, v144, v145
	v_cvt_pk_bf16_f32 v163, v146, v147
	s_nop 0
	v_permlane32_swap_b32_e32 v148, v150
	v_permlane32_swap_b32_e32 v149, v151
	v_permlane32_swap_b32_e32 v152, v154
	v_permlane32_swap_b32_e32 v153, v155
	v_permlane32_swap_b32_e32 v156, v158
	v_permlane32_swap_b32_e32 v157, v159
	v_permlane32_swap_b32_e32 v160, v162
	v_permlane32_swap_b32_e32 v161, v163
	ds_read_b64_tr_b16 v[172:173], v185 offset:0
	ds_read_b64_tr_b16 v[174:175], v185 offset:0x800
	ds_read_b64_tr_b16 v[202:203], v185 offset:0x1000
	ds_read_b64_tr_b16 v[204:205], v185 offset:0x1800
	ds_read_b64_tr_b16 v[206:207], v185 offset:0x2000
	ds_read_b64_tr_b16 v[208:209], v185 offset:0x2800
	ds_read_b64_tr_b16 v[224:225], v185 offset:0x3000
	ds_read_b64_tr_b16 v[226:227], v185 offset:0x3800
	s_waitcnt lgkmcnt(0)
; __device__ __forceinline__ void mask_tile(f32x16& p0, f32x16& p1, int dq, unsigned W) {
;     const float NEG = -__builtin_inff();
; #pragma unroll
;     for (int r = 0; r < 16; ++r) {
;         const int c = (r & 3) + 8 * (r >> 2);
;         if ((unsigned)(dq - c) >= W) p0[r] = NEG;
;         if ((unsigned)(dq - c - 32) >= W) p1[r] = NEG;
;     }
; }
; template <int VB>
; __device__ __forceinline__ void pv_tile(f32x16* o, int vb0, bf16x8 pa0, bf16x8 pa1, bf16x8 pa2, bf16x8 pa3) {
;     ...
;     PV_D0(0); PV_D0(1); PV_D0(2); PV_D0(3);
	s_nop 0
	v_mfma_f32_32x32x16_bf16 v[50:65], v[148:151], v[172:175], v[50:65]
	ds_read_b64_tr_b16 v[172:173], v185 offset:0x200
	ds_read_b64_tr_b16 v[174:175], v185 offset:0xa00
	v_mfma_f32_32x32x16_bf16 v[50:65], v[152:155], v[202:205], v[50:65]
	ds_read_b64_tr_b16 v[202:203], v185 offset:0x1200
	ds_read_b64_tr_b16 v[204:205], v185 offset:0x1a00
	v_mfma_f32_32x32x16_bf16 v[50:65], v[156:159], v[206:209], v[50:65]
	ds_read_b64_tr_b16 v[206:207], v185 offset:0x2200
	ds_read_b64_tr_b16 v[208:209], v185 offset:0x2a00
	v_mfma_f32_32x32x16_bf16 v[50:65], v[160:163], v[224:227], v[50:65]
	ds_read_b64_tr_b16 v[224:225], v185 offset:0x3200
	ds_read_b64_tr_b16 v[226:227], v185 offset:0x3a00
	s_waitcnt lgkmcnt(0)
	v_mfma_f32_32x32x16_bf16 v[34:49], v[148:151], v[172:175], v[34:49]
	ds_read_b64_tr_b16 v[172:173], v185 offset:0x400
	ds_read_b64_tr_b16 v[174:175], v185 offset:0xc00
	v_mfma_f32_32x32x16_bf16 v[34:49], v[152:155], v[202:205], v[34:49]
	ds_read_b64_tr_b16 v[202:203], v185 offset:0x1400
	ds_read_b64_tr_b16 v[204:205], v185 offset:0x1c00
	v_mfma_f32_32x32x16_bf16 v[34:49], v[156:159], v[206:209], v[34:49]
	ds_read_b64_tr_b16 v[206:207], v185 offset:0x2400
	ds_read_b64_tr_b16 v[208:209], v185 offset:0x2c00
	v_mfma_f32_32x32x16_bf16 v[34:49], v[160:163], v[224:227], v[34:49]
	ds_read_b64_tr_b16 v[224:225], v185 offset:0x3400
	ds_read_b64_tr_b16 v[226:227], v185 offset:0x3c00
	s_waitcnt lgkmcnt(0)
	v_mfma_f32_32x32x16_bf16 v[18:33], v[148:151], v[172:175], v[18:33]
	ds_read_b64_tr_b16 v[172:173], v185 offset:0x600
	ds_read_b64_tr_b16 v[174:175], v185 offset:0xe00
	v_mfma_f32_32x32x16_bf16 v[18:33], v[152:155], v[202:205], v[18:33]
	ds_read_b64_tr_b16 v[202:203], v185 offset:0x1600
	ds_read_b64_tr_b16 v[204:205], v185 offset:0x1e00
	v_mfma_f32_32x32x16_bf16 v[18:33], v[156:159], v[206:209], v[18:33]
	ds_read_b64_tr_b16 v[206:207], v185 offset:0x2600
	ds_read_b64_tr_b16 v[208:209], v185 offset:0x2e00
	v_mfma_f32_32x32x16_bf16 v[18:33], v[160:163], v[224:227], v[18:33]
	ds_read_b64_tr_b16 v[224:225], v185 offset:0x3600
	ds_read_b64_tr_b16 v[226:227], v185 offset:0x3e00
	s_waitcnt lgkmcnt(0)
	v_mfma_f32_32x32x16_bf16 v[2:17], v[148:151], v[172:175], v[2:17]
	s_cmp_le_i32 s7, s6
	v_mfma_f32_32x32x16_bf16 v[2:17], v[152:155], v[202:205], v[2:17]
	v_mfma_f32_32x32x16_bf16 v[2:17], v[156:159], v[206:209], v[2:17]
	v_mfma_f32_32x32x16_bf16 v[2:17], v[160:163], v[224:227], v[2:17]
	s_cbranch_scc1 .LBB0_91
	v_add_u32_e32 v148, 0x4000007b, v197
	v_cmp_gt_u32_e32 vcc, 2.0, v148
	v_add_u32_e32 v148, 0x5b, v197
	s_nop 0
	v_cndmask_b32_e32 v82, v220, v82, vcc
	v_cmp_lt_u32_e32 vcc, s33, v148
	v_add_u32_e32 v148, 0x7a, v197
	s_nop 0
	v_cndmask_b32_e32 v66, v220, v66, vcc
	v_cmp_lt_u32_e32 vcc, s33, v148
	v_add_u32_e32 v148, 0x5a, v197
	s_nop 0
	v_cndmask_b32_e32 v83, v220, v83, vcc
	v_cmp_lt_u32_e32 vcc, s33, v148
	v_add_u32_e32 v148, 0x79, v197
	s_nop 0
	v_cndmask_b32_e32 v67, v220, v67, vcc
	v_cmp_lt_u32_e32 vcc, s33, v148
	v_add_u32_e32 v148, 0x59, v197
	s_nop 0
	v_cndmask_b32_e32 v84, v220, v84, vcc
	v_cmp_lt_u32_e32 vcc, s33, v148
	v_add_u32_e32 v148, 0x78, v197
	s_nop 0
	v_cndmask_b32_e32 v68, v220, v68, vcc
	v_cmp_lt_u32_e32 vcc, s33, v148
	v_add_u32_e32 v148, 0x58, v197
	s_nop 0
	v_cndmask_b32_e32 v85, v220, v85, vcc
	v_cmp_lt_u32_e32 vcc, s33, v148
	v_add_u32_e32 v148, 0x73, v197
	s_nop 0
	v_cndmask_b32_e32 v69, v220, v69, vcc
	v_cmp_lt_u32_e32 vcc, s33, v148
	v_add_u32_e32 v148, 0x53, v197
	s_nop 0
	v_cndmask_b32_e32 v86, v220, v86, vcc
	v_cmp_lt_u32_e32 vcc, s33, v148
	v_add_u32_e32 v148, 0x72, v197
	s_nop 0
	v_cndmask_b32_e32 v70, v220, v70, vcc
	v_cmp_lt_u32_e32 vcc, s33, v148
	v_add_u32_e32 v148, 0x52, v197
	s_nop 0
	v_cndmask_b32_e32 v87, v220, v87, vcc
	v_cmp_lt_u32_e32 vcc, s33, v148
	v_add_u32_e32 v148, 0x71, v197
	s_nop 0
	v_cndmask_b32_e32 v71, v220, v71, vcc
	v_cmp_lt_u32_e32 vcc, s33, v148
	v_add_u32_e32 v148, 0x51, v197
	s_nop 0
	v_cndmask_b32_e32 v88, v220, v88, vcc
	v_cmp_lt_u32_e32 vcc, s33, v148
	v_add_u32_e32 v148, 0x70, v197
	s_nop 0
	v_cndmask_b32_e32 v72, v220, v72, vcc
	v_cmp_lt_u32_e32 vcc, s33, v148
	v_add_u32_e32 v148, 0x50, v197
	s_nop 0
	v_cndmask_b32_e32 v89, v220, v89, vcc
	v_cmp_lt_u32_e32 vcc, s33, v148
	v_add_u32_e32 v148, 0x6b, v197
	s_nop 0
	v_cndmask_b32_e32 v73, v220, v73, vcc
	v_cmp_lt_u32_e32 vcc, s33, v148
	v_add_u32_e32 v148, 0x4b, v197
	s_nop 0
	v_cndmask_b32_e32 v90, v220, v90, vcc
	v_cmp_lt_u32_e32 vcc, s33, v148
	v_add_u32_e32 v148, 0x6a, v197
	s_nop 0
	v_cndmask_b32_e32 v74, v220, v74, vcc
	v_cmp_lt_u32_e32 vcc, s33, v148
	v_add_u32_e32 v148, 0x4a, v197
	s_nop 0
	v_cndmask_b32_e32 v91, v220, v91, vcc
	v_cmp_lt_u32_e32 vcc, s33, v148
	v_add_u32_e32 v148, 0x69, v197
	s_nop 0
	v_cndmask_b32_e32 v75, v220, v75, vcc
	v_cmp_lt_u32_e32 vcc, s33, v148
	v_add_u32_e32 v148, 0x49, v197
	s_nop 0
	v_cndmask_b32_e32 v92, v220, v92, vcc
	v_cmp_lt_u32_e32 vcc, s33, v148
	v_add_u32_e32 v148, 0x68, v197
	s_nop 0
	v_cndmask_b32_e32 v76, v220, v76, vcc
	v_cmp_lt_u32_e32 vcc, s33, v148
	v_add_u32_e32 v148, 0x48, v197
	s_nop 0
	v_cndmask_b32_e32 v93, v220, v93, vcc
	v_cmp_lt_u32_e32 vcc, s33, v148
	v_add_u32_e32 v148, 0x63, v197
	s_nop 0
	v_cndmask_b32_e32 v77, v220, v77, vcc
	v_cmp_lt_u32_e32 vcc, s33, v148
	v_add_u32_e32 v148, 0x43, v197
	s_nop 0
	v_cndmask_b32_e32 v94, v220, v94, vcc
	v_cmp_lt_u32_e32 vcc, s33, v148
	v_add_u32_e32 v148, 0x62, v197
	s_nop 0
	v_cndmask_b32_e32 v78, v220, v78, vcc
	v_cmp_lt_u32_e32 vcc, s33, v148
	v_add_u32_e32 v148, 0x42, v197
	s_nop 0
	v_cndmask_b32_e32 v95, v220, v95, vcc
	v_cmp_lt_u32_e32 vcc, s33, v148
	v_add_u32_e32 v148, 0x61, v197
	s_nop 0
	v_cndmask_b32_e32 v79, v220, v79, vcc
	v_cmp_lt_u32_e32 vcc, s33, v148
	v_add_u32_e32 v148, 0x41, v197
	s_nop 0
	v_cndmask_b32_e32 v96, v220, v96, vcc
	v_cmp_lt_u32_e32 vcc, s33, v148
	v_add_u32_e32 v148, 0x60, v197
	s_nop 0
	v_cndmask_b32_e32 v80, v220, v80, vcc
	v_cmp_lt_u32_e32 vcc, s33, v148
	v_add_u32_e32 v148, 64, v197
	s_nop 0
	v_cndmask_b32_e32 v97, v220, v97, vcc
	v_cmp_lt_u32_e32 vcc, s33, v148
	s_nop 1
	v_cndmask_b32_e32 v81, v220, v81, vcc
; __device__ __forceinline__ void partialSM(f32x16& p0, f32x16& p1, float& m_reg, float& mn, float& alpha, bool rs) {
;     float pmax = p0[0]; for (int r = 1; r < 16; ++r) pmax = fmaxf(pmax, p0[r]); for (int r = 0; r < 16; ++r) pmax = fmaxf(pmax, p1[r]);
;     if (!rs) pmax = -__builtin_inff();
;     { auto rr = __builtin_amdgcn_permlane32_swap(__float_as_uint(pmax), __float_as_uint(pmax), false, false);
;       pmax = fmaxf(__uint_as_float(rr[0]), __uint_as_float(rr[1])); }
;     constexpr float C2 = 1.4426950408889634f * SCALE;
;     if (__builtin_expect(__all((pmax - m_reg) * SCALE <= THR), 1)) { mn = m_reg; alpha = 1.f; }
;     else { mn = fmaxf(m_reg, pmax); alpha = __builtin_amdgcn_exp2f((m_reg - mn) * C2); m_reg = mn; }
;     const float mnL = rs ? -mn * C2 : -__builtin_inff();
;     for (int r = 0; r < 16; ++r) p0[r] = fmaf(p0[r], C2, mnL); for (int r = 0; r < 16; ++r) p1[r] = fmaf(p1[r], C2, mnL);
;     for (int r = 0; r < 16; ++r) p0[r] = __builtin_amdgcn_exp2f(p0[r]);
.LBB0_91:
	s_add_i32 s0, s3, -2
	s_lshr_b32 s8, s0, 2
	s_cmp_ge_i32 s8, s44
	s_cselect_b64 s[0:1], -1, 0
	s_lshl_b32 s8, 1, s8
	v_and_b32_e32 v148, s8, v165
	v_cmp_ne_u32_e32 vcc, 0, v148
	v_max_f32_e32 v148, v83, v83
	v_max_f32_e32 v149, v82, v82
	v_max_f32_e32 v148, v149, v148
	v_max3_f32 v148, v148, v84, v85
	v_max3_f32 v148, v148, v86, v87
	v_max3_f32 v148, v148, v88, v89
	v_max3_f32 v148, v148, v90, v91
	v_max3_f32 v148, v148, v92, v93
	v_max3_f32 v148, v148, v94, v95
	v_max3_f32 v148, v148, v96, v97
	v_max3_f32 v148, v148, v66, v67
	v_max3_f32 v148, v148, v68, v69
	v_max3_f32 v148, v148, v70, v71
	v_max3_f32 v148, v148, v72, v73
	v_max3_f32 v148, v148, v74, v75
	v_max3_f32 v148, v148, v76, v77
	v_max3_f32 v148, v148, v78, v79
	s_or_b64 s[40:41], s[0:1], vcc
	v_max3_f32 v148, v148, v80, v81
	v_cndmask_b32_e64 v148, v220, v148, s[40:41]
	v_mov_b32_e32 v149, v148
	s_nop 1
	v_permlane32_swap_b32_e32 v148, v149
	v_max_f32_e32 v149, v149, v149
	v_max_f32_e32 v148, v148, v148
	v_max_f32_e32 v148, v148, v149
	v_sub_f32_e32 v149, v148, v198
	v_mul_f32_e32 v149, 0x3db504f3, v149
	v_cmp_ge_f32_e32 vcc, s91, v149
	v_max_f32_e32 v149, v198, v198
	v_max_f32_e32 v148, v149, v148
	v_sub_f32_e32 v149, v198, v148
	v_mul_f32_e32 v149, 0x3e0293ee, v149
	v_exp_f32_e32 v149, v149
	s_cmp_eq_u64 vcc, exec
	s_cselect_b64 s[42:43], -1, 0
	s_barrier
	s_waitcnt vmcnt(0)
	v_cndmask_b32_e64 v202, v149, 1.0, s[42:43]
	v_cmp_gt_f32_e32 vcc, 1.0, v202
	s_waitcnt vmcnt(3)
	ds_write_b128 v191, v[234:237]
	s_waitcnt vmcnt(2)
	ds_write_b128 v192, v[238:241]
	s_waitcnt vmcnt(1)
	ds_write_b128 v188, v[242:245] offset:32768
	s_waitcnt vmcnt(0)
	ds_write_b128 v188, v[246:249] offset:40960
	s_cbranch_vccz .LBB0_95
	s_and_saveexec_b64 s[0:1], s[38:39]
	ds_write_b32 v187, v202 offset:128
	s_or_b64 exec, exec, s[0:1]
	s_waitcnt lgkmcnt(0)
	ds_read_b128 v[150:153], v186 offset:224
	ds_read_b128 v[154:157], v186 offset:192
	ds_read_b128 v[158:161], v186 offset:160
	ds_read_b128 v[172:175], v186 offset:128
	s_waitcnt lgkmcnt(3)
	v_pk_mul_f32 v[64:65], v[64:65], v[152:153]
	s_waitcnt lgkmcnt(2)
	v_pk_mul_f32 v[60:61], v[60:61], v[156:157]
	s_waitcnt lgkmcnt(1)
	v_pk_mul_f32 v[56:57], v[56:57], v[160:161]
	s_waitcnt lgkmcnt(0)
	v_pk_mul_f32 v[52:53], v[52:53], v[174:175]
	v_pk_mul_f32 v[62:63], v[62:63], v[150:151]
	v_pk_mul_f32 v[58:59], v[58:59], v[154:155]
	v_pk_mul_f32 v[54:55], v[54:55], v[158:159]
	v_pk_mul_f32 v[50:51], v[50:51], v[172:173]
	v_pk_mul_f32 v[48:49], v[48:49], v[152:153]
	v_pk_mul_f32 v[44:45], v[44:45], v[156:157]
	v_pk_mul_f32 v[40:41], v[40:41], v[160:161]
	v_pk_mul_f32 v[36:37], v[36:37], v[174:175]
	v_pk_mul_f32 v[46:47], v[46:47], v[150:151]
	v_pk_mul_f32 v[42:43], v[42:43], v[154:155]
	v_pk_mul_f32 v[38:39], v[38:39], v[158:159]
	v_pk_mul_f32 v[34:35], v[34:35], v[172:173]
	v_pk_mul_f32 v[32:33], v[32:33], v[152:153]
	v_pk_mul_f32 v[28:29], v[28:29], v[156:157]
	v_pk_mul_f32 v[24:25], v[24:25], v[160:161]
	v_pk_mul_f32 v[20:21], v[20:21], v[174:175]
	v_pk_mul_f32 v[30:31], v[30:31], v[150:151]
	v_pk_mul_f32 v[26:27], v[26:27], v[154:155]
	v_pk_mul_f32 v[22:23], v[22:23], v[158:159]
	v_pk_mul_f32 v[18:19], v[18:19], v[172:173]
	v_pk_mul_f32 v[16:17], v[16:17], v[152:153]
	v_pk_mul_f32 v[12:13], v[12:13], v[156:157]
	v_pk_mul_f32 v[8:9], v[8:9], v[160:161]
	v_pk_mul_f32 v[4:5], v[4:5], v[174:175]
	v_pk_mul_f32 v[14:15], v[14:15], v[150:151]
	v_pk_mul_f32 v[10:11], v[10:11], v[154:155]
	v_pk_mul_f32 v[6:7], v[6:7], v[158:159]
	v_pk_mul_f32 v[2:3], v[2:3], v[172:173]
.LBB0_95:
	v_cndmask_b32_e64 v179, v148, v198, s[42:43]
	v_mul_f32_e32 v148, 0xbe0293ee, v179
	v_cndmask_b32_e64 v180, v220, v148, s[40:41]
	v_fmamk_f32 v82, v82, 0x3e0293ee, v180
	v_fmamk_f32 v83, v83, 0x3e0293ee, v180
	v_fmamk_f32 v84, v84, 0x3e0293ee, v180
	v_fmamk_f32 v85, v85, 0x3e0293ee, v180
	v_fmamk_f32 v86, v86, 0x3e0293ee, v180
	v_fmamk_f32 v87, v87, 0x3e0293ee, v180
	v_fmamk_f32 v88, v88, 0x3e0293ee, v180
	v_fmamk_f32 v89, v89, 0x3e0293ee, v180
	v_fmamk_f32 v90, v90, 0x3e0293ee, v180
	v_fmamk_f32 v91, v91, 0x3e0293ee, v180
	v_fmamk_f32 v92, v92, 0x3e0293ee, v180
	v_fmamk_f32 v93, v93, 0x3e0293ee, v180
	v_fmamk_f32 v94, v94, 0x3e0293ee, v180
	v_fmamk_f32 v95, v95, 0x3e0293ee, v180
	v_fmamk_f32 v96, v96, 0x3e0293ee, v180
	v_fmamk_f32 v97, v97, 0x3e0293ee, v180
	v_exp_f32_e32 v148, v82
	v_exp_f32_e32 v163, v83
	v_exp_f32_e32 v149, v84
	v_exp_f32_e32 v162, v85
	v_exp_f32_e32 v150, v86
	v_exp_f32_e32 v161, v87
	v_exp_f32_e32 v151, v88
	v_exp_f32_e32 v160, v89
	v_exp_f32_e32 v152, v90
	v_exp_f32_e32 v159, v91
	v_exp_f32_e32 v153, v92
	v_exp_f32_e32 v158, v93
	v_exp_f32_e32 v154, v94
	v_exp_f32_e32 v157, v95
	v_exp_f32_e32 v155, v96
	v_exp_f32_e32 v156, v97
	v_fmamk_f32 v203, v73, 0x3e0293ee, v180
	v_fmamk_f32 v204, v74, 0x3e0293ee, v180
	v_fmamk_f32 v208, v66, 0x3e0293ee, v180
	v_fmamk_f32 v209, v67, 0x3e0293ee, v180
	v_fmamk_f32 v223, v68, 0x3e0293ee, v180
	v_fmamk_f32 v224, v69, 0x3e0293ee, v180
	v_fmamk_f32 v225, v70, 0x3e0293ee, v180
	v_fmamk_f32 v198, v71, 0x3e0293ee, v180
	v_fmamk_f32 v201, v72, 0x3e0293ee, v180
	v_fmamk_f32 v205, v75, 0x3e0293ee, v180
	v_fmamk_f32 v206, v76, 0x3e0293ee, v180
	v_fmamk_f32 v207, v77, 0x3e0293ee, v180
	v_fmamk_f32 v181, v78, 0x3e0293ee, v180
	v_fmamk_f32 v226, v79, 0x3e0293ee, v180
	v_fmamk_f32 v227, v80, 0x3e0293ee, v180
	v_fmac_f32_e32 v180, 0x3e0293ee, v81
	s_waitcnt lgkmcnt(0)
	s_barrier
	s_cmp_lt_u32 s3, s2
	s_cselect_b64 s[22:23], -1, 0
	s_cmp_ge_u32 s3, s2
	s_cbranch_scc1 .Lmy_hs2_noload
	v_add_u32_e32 v234, 0x41, v250
	v_add_u32_e32 v236, 0x61, v250
	v_ashrrev_i32_e32 v235, 31, v234
	v_ashrrev_i32_e32 v237, 31, v236
	v_lshlrev_b64 v[242:243], 8, v[234:235]
	v_lshlrev_b64 v[244:245], 8, v[236:237]
	v_lshl_add_u64 v[234:235], v[170:171], 0, v[242:243]
	v_lshl_add_u64 v[238:239], v[170:171], 0, v[244:245]
	v_lshl_add_u64 v[242:243], v[176:177], 0, v[242:243]
	v_lshl_add_u64 v[246:247], v[176:177], 0, v[244:245]
	global_load_dwordx4 v[234:237], v[234:235], off
	s_nop 0
	global_load_dwordx4 v[238:241], v[238:239], off
	s_nop 0
	global_load_dwordx4 v[242:245], v[242:243], off
	s_nop 0
	global_load_dwordx4 v[246:249], v[246:247], off
; __device__ __forceinline__ void finishSM(f32x16& p0, f32x16& p1, float alpha, float& l_reg, bf16x8& pa0, bf16x8& pa1, bf16x8& pa2, bf16x8& pa3) {
;     for (int r = 0; r < 16; ++r) p1[r] = __builtin_amdgcn_exp2f(p1[r]);
;     float ps = 0; for (int r = 0; r < 16; ++r) ps += p0[r]; for (int r = 0; r < 16; ++r) ps += p1[r];
;     { auto rr = __builtin_amdgcn_permlane32_swap(__float_as_uint(ps), __float_as_uint(ps), false, false);
;       ps = __uint_as_float(rr[0]) + __uint_as_float(rr[1]); }
;     l_reg = l_reg * alpha + ps;
;     ...
;     PK4(p0, 0, pa0); PK4(p0, 8, pa1); PK4(p1, 0, pa2); PK4(p1, 8, pa3);
;     ...
; }
; template <int KB>
; __device__ __forceinline__ void qkt(f32x16& p0, f32x16& p1, const char* K_lds, int r32, int hi, const bf16x8* qr) {
;     p0 = f32x16{}; p1 = f32x16{};
;     const char* kb[4];
; #pragma unroll
;     for (int dd = 0; dd < 4; ++dd) kb[dd] = K_lds + KB * SHM_K + KSWZ(r32, (dd * 16 + hi * 8) * 2);
; #pragma unroll
;     for (int d0 = 0; d0 < 8; ++d0) { const char* a = kb[d0 & 3] + (d0 >> 2) * 128;
;         bf16x8 b0 = *reinterpret_cast<const bf16x8*>(a);
;         bf16x8 b1 = *reinterpret_cast<const bf16x8*>(a + 32 * 256);
;         p0 = __builtin_amdgcn_mfma_f32_32x32x16_bf16(b0, qr[d0], p0, 0, 0, 0);
;         p1 = __builtin_amdgcn_mfma_f32_32x32x16_bf16(b1, qr[d0], p1, 0, 0, 0); }
; }
.Lmy_hs2_noload:
	ds_read_b128 v[66:69], v169 offset:32768
	ds_read_b128 v[70:73], v169 offset:40960
	ds_read_b128 v[172:175], v193 offset:32768
	ds_read_b128 v[228:231], v193 offset:40960
	v_exp_f32_e32 v198, v198
	v_exp_f32_e32 v201, v201
	s_waitcnt lgkmcnt(3)
	v_mfma_f32_32x32x16_bf16 v[82:97], v[66:69], v[132:135], 0
	v_exp_f32_e32 v214, v204
	v_exp_f32_e32 v205, v205
	v_exp_f32_e32 v206, v206
	v_exp_f32_e32 v207, v207
	v_exp_f32_e32 v181, v181
	v_exp_f32_e32 v215, v226
	v_exp_f32_e32 v216, v227
	s_waitcnt lgkmcnt(2)
	v_mfma_f32_32x32x16_bf16 v[66:81], v[70:73], v[132:135], 0
	v_exp_f32_e32 v180, v180
	s_waitcnt lgkmcnt(1)
	v_mfma_f32_32x32x16_bf16 v[82:97], v[172:175], v[128:131], v[82:97]
	s_waitcnt lgkmcnt(0)
	v_mfma_f32_32x32x16_bf16 v[66:81], v[228:231], v[128:131], v[66:81]
	ds_read_b128 v[172:175], v194 offset:32768
	ds_read_b128 v[228:231], v194 offset:40960
	s_waitcnt lgkmcnt(1)
	v_mfma_f32_32x32x16_bf16 v[82:97], v[172:175], v[124:127], v[82:97]
	s_waitcnt lgkmcnt(0)
	v_mfma_f32_32x32x16_bf16 v[66:81], v[228:231], v[124:127], v[66:81]
	ds_read_b128 v[172:175], v195 offset:32768
	ds_read_b128 v[228:231], v195 offset:40960
	s_waitcnt lgkmcnt(1)
	v_mfma_f32_32x32x16_bf16 v[82:97], v[172:175], v[120:123], v[82:97]
	s_waitcnt lgkmcnt(0)
	v_mfma_f32_32x32x16_bf16 v[66:81], v[228:231], v[120:123], v[66:81]
	ds_read_b128 v[172:175], v169 offset:32896
	ds_read_b128 v[228:231], v169 offset:41088
	s_waitcnt lgkmcnt(1)
	v_mfma_f32_32x32x16_bf16 v[82:97], v[172:175], v[116:119], v[82:97]
	s_waitcnt lgkmcnt(0)
	v_mfma_f32_32x32x16_bf16 v[66:81], v[228:231], v[116:119], v[66:81]
	ds_read_b128 v[172:175], v193 offset:32896
	ds_read_b128 v[228:231], v193 offset:41088
	s_waitcnt lgkmcnt(1)
	v_mfma_f32_32x32x16_bf16 v[82:97], v[172:175], v[112:115], v[82:97]
	s_waitcnt lgkmcnt(0)
	v_mfma_f32_32x32x16_bf16 v[66:81], v[228:231], v[112:115], v[66:81]
	ds_read_b128 v[172:175], v194 offset:32896
	ds_read_b128 v[228:231], v194 offset:41088
	s_waitcnt lgkmcnt(1)
	v_mfma_f32_32x32x16_bf16 v[82:97], v[172:175], v[108:111], v[82:97]
	s_waitcnt lgkmcnt(0)
	v_mfma_f32_32x32x16_bf16 v[66:81], v[228:231], v[108:111], v[66:81]
	ds_read_b128 v[172:175], v195 offset:32896
	ds_read_b128 v[228:231], v195 offset:41088
	s_waitcnt lgkmcnt(1)
	v_mfma_f32_32x32x16_bf16 v[82:97], v[172:175], v[104:107], v[82:97]
	v_exp_f32_e32 v173, v209
	v_exp_f32_e32 v209, v203
	v_add_f32_e32 v203, 0, v148
	v_add_f32_e32 v203, v163, v203
	v_add_f32_e32 v203, v149, v203
	v_add_f32_e32 v203, v162, v203
	v_add_f32_e32 v203, v150, v203
	v_add_f32_e32 v203, v161, v203
	v_add_f32_e32 v203, v151, v203
	v_add_f32_e32 v203, v160, v203
	v_add_f32_e32 v203, v152, v203
	v_add_f32_e32 v203, v159, v203
	v_add_f32_e32 v203, v153, v203
	v_add_f32_e32 v203, v158, v203
	v_exp_f32_e32 v172, v208
	v_add_f32_e32 v203, v154, v203
	v_add_f32_e32 v203, v157, v203
	v_exp_f32_e32 v174, v223
	v_add_f32_e32 v203, v155, v203
	v_exp_f32_e32 v175, v224
	v_add_f32_e32 v203, v156, v203
	v_exp_f32_e32 v208, v225
	v_add_f32_e32 v203, v172, v203
	v_add_f32_e32 v203, v173, v203
	v_add_f32_e32 v203, v174, v203
	v_add_f32_e32 v203, v175, v203
	v_add_f32_e32 v203, v208, v203
	v_add_f32_e32 v203, v198, v203
	v_add_f32_e32 v203, v201, v203
	v_add_f32_e32 v203, v209, v203
	v_add_f32_e32 v203, v214, v203
	v_add_f32_e32 v203, v205, v203
	s_waitcnt lgkmcnt(0)
	v_mfma_f32_32x32x16_bf16 v[66:81], v[228:231], v[104:107], v[66:81]
	v_add_f32_e32 v203, v206, v203
	v_add_f32_e32 v203, v207, v203
	v_add_f32_e32 v203, v181, v203
	v_add_f32_e32 v203, v215, v203
	v_add_f32_e32 v203, v216, v203
	v_add_f32_e32 v203, v180, v203
	v_mov_b32_e32 v204, v203
	v_cvt_pk_bf16_f32 v148, v148, v163
	v_cvt_pk_bf16_f32 v149, v149, v162
	v_cvt_pk_bf16_f32 v150, v150, v161
	v_cvt_pk_bf16_f32 v151, v151, v160
	v_cvt_pk_bf16_f32 v152, v152, v159
	v_cvt_pk_bf16_f32 v153, v153, v158
	v_cvt_pk_bf16_f32 v154, v154, v157
	v_cvt_pk_bf16_f32 v155, v155, v156
	v_cvt_pk_bf16_f32 v156, v172, v173
	v_cvt_pk_bf16_f32 v157, v174, v175
	v_cvt_pk_bf16_f32 v158, v208, v198
	v_cvt_pk_bf16_f32 v159, v201, v209
	v_cvt_pk_bf16_f32 v160, v214, v205
	v_cvt_pk_bf16_f32 v161, v206, v207
	v_cvt_pk_bf16_f32 v162, v181, v215
	v_cvt_pk_bf16_f32 v163, v216, v180
	s_nop 1
	v_permlane32_swap_b32_e32 v203, v204
	v_permlane32_swap_b32_e32 v148, v150
	v_permlane32_swap_b32_e32 v149, v151
	v_permlane32_swap_b32_e32 v152, v154
	v_permlane32_swap_b32_e32 v153, v155
	v_permlane32_swap_b32_e32 v156, v158
	v_permlane32_swap_b32_e32 v157, v159
	v_permlane32_swap_b32_e32 v160, v162
	v_permlane32_swap_b32_e32 v161, v163

; __device__ __forceinline__ void partialSM(f32x16& p0, f32x16& p1, float& m_reg, float& mn, float& alpha, bool rs) {
;     float pmax = p0[0]; for (int r = 1; r < 16; ++r) pmax = fmaxf(pmax, p0[r]); for (int r = 0; r < 16; ++r) pmax = fmaxf(pmax, p1[r]);
;     if (!rs) pmax = -__builtin_inff();
;     { auto rr = __builtin_amdgcn_permlane32_swap(__float_as_uint(pmax), __float_as_uint(pmax), false, false);
;       pmax = fmaxf(__uint_as_float(rr[0]), __uint_as_float(rr[1])); }
;     constexpr float C2 = 1.4426950408889634f * SCALE;
;     if (__builtin_expect(__all((pmax - m_reg) * SCALE <= THR), 1)) { mn = m_reg; alpha = 1.f; }
.LBB0_99:
	s_add_i32 s0, s3, -1
	s_lshr_b32 s8, s0, 2
	s_cmp_ge_i32 s8, s44
	s_cselect_b64 s[0:1], -1, 0
	s_lshl_b32 s8, 1, s8
	v_and_b32_e32 v148, s8, v165
	v_cmp_ne_u32_e32 vcc, 0, v148
	v_max_f32_e32 v148, v83, v83
	v_max_f32_e32 v149, v82, v82
	v_max_f32_e32 v148, v149, v148
	v_max3_f32 v148, v148, v84, v85
	v_max3_f32 v148, v148, v86, v87
	v_max3_f32 v148, v148, v88, v89
	v_max3_f32 v148, v148, v90, v91
	v_max3_f32 v148, v148, v92, v93
	v_max3_f32 v148, v148, v94, v95
	v_max3_f32 v148, v148, v96, v97
	v_max3_f32 v148, v148, v66, v67
	v_max3_f32 v148, v148, v68, v69
	v_max3_f32 v148, v148, v70, v71
	v_max3_f32 v148, v148, v72, v73
	v_max3_f32 v148, v148, v74, v75
	v_max3_f32 v148, v148, v76, v77
	v_max3_f32 v148, v148, v78, v79
	v_max3_f32 v148, v148, v80, v81
	s_or_b64 s[40:41], s[0:1], vcc
	v_cndmask_b32_e64 v148, v220, v148, s[40:41]
	v_mov_b32_e32 v149, v148
	s_nop 1
	v_permlane32_swap_b32_e32 v148, v149
	v_max_f32_e32 v149, v149, v149
	v_max_f32_e32 v148, v148, v148
	v_max_f32_e32 v148, v148, v149
	v_sub_f32_e32 v149, v148, v179
	v_mul_f32_e32 v149, 0x3db504f3, v149
	v_cmp_ge_f32_e32 vcc, s91, v149
	s_cmp_eq_u64 vcc, exec
	s_cselect_b64 s[42:43], -1, 0
	s_andn2_b64 vcc, exec, s[22:23]
	s_barrier
	s_cbranch_vccnz .LBB0_101
	s_waitcnt vmcnt(0)
	s_waitcnt vmcnt(3)
	ds_write_b128 v191, v[234:237] offset:16384
	s_waitcnt vmcnt(2)
	ds_write_b128 v192, v[238:241] offset:16384
	s_waitcnt vmcnt(1)
	ds_write_b128 v188, v[242:245] offset:49152
	s_waitcnt vmcnt(0)
	ds_write_b128 v188, v[246:249] offset:57344
